# attention S(0): K-fragment addresses formed first, eight LDS reads issued back to back, each MFMA waits for its own fragment
# baseline (speedup 1.0000x reference)
.LBB0_896:
	s_andn2_saveexec_b64 s[44:45], s[44:45]
	s_cbranch_execz .LBB0_876
	v_mov_b32_e32 v129, v250
	v_lshrrev_b32_e32 v168, 1, v250
	v_and_b32_e32 v168, 0xe0, v168
	v_and_b32_e32 v169, 31, v250
	v_or_b32_e32 v168, v168, v169
	v_mul_u32_u24_e32 v168, 0x1200, v168
	v_bfe_u32 v169, v250, 5, 1
	v_lshl_or_b32 v168, v169, 4, v168
	v_lshrrev_b32_e32 v169, 3, v250
	v_and_b32_e32 v171, 7, v250
	v_mul_u32_u24_e32 v170, 0x1200, v169
	v_lshl_or_b32 v170, v171, 4, v170
	s_lshl_b32 s18, s8, 1
	v_mul_lo_u32 v169, s18, v169
	v_lshl_or_b32 v169, v171, 4, v169
	v_lshrrev_b32_e32 v171, 6, v250
	v_lshlrev_b32_e32 v171, 10, v171
	v_and_b32_e32 v172, 63, v250
	v_lshlrev_b32_e32 v172, 4, v172
	v_lshrrev_b32_e32 v173, 6, v250
	v_lshl_or_b32 v172, v173, 10, v172
	v_add_u32_e32 v173, 0x10000, v172
	s_waitcnt lgkmcnt(0)
	s_barrier
	v_readlane_b32 s9, v254, 52
	v_lshlrev_b32_e32 v2, 4, v129
	v_lshlrev_b32_e32 v3, 1, v129
	v_lshrrev_b32_e32 v131, 1, v129
	v_lshlrev_b32_e32 v0, 3, v129
	v_xor_b32_e32 v4, v2, v129
	v_and_b32_e32 v2, 19, v129
	v_and_b32_e32 v3, 8, v3
	v_and_b32_e32 v5, 4, v131
	v_ashrrev_i32_e32 v128, 3, v129
	v_and_b32_e32 v130, 56, v0
	v_or3_b32 v5, v3, v2, v5
	v_mov_b64_e32 v[2:3], s[40:41]
	v_mad_i64_i32 v[0:1], s[2:3], v128, s21, 0
	v_lshlrev_b32_e32 v176, 1, v130
	v_mad_i64_i32 v[2:3], s[2:3], v128, s33, v[2:3]
	v_lshl_add_u64 v[132:133], v[2:3], 0, v[176:177]
	v_lshlrev_b32_e32 v2, 7, v128
	s_movk_i32 s2, 0x70
	v_and_or_b32 v142, v4, s2, v2
	s_mov_b32 s2, 0xd8000
	v_lshl_add_u64 v[0:1], v[0:1], 1, s[42:43]
	v_add_co_u32_e32 v2, vcc, s2, v132
	v_lshl_add_u64 v[0:1], v[0:1], 0, v[176:177]
	v_lshrrev_b32_e32 v40, 1, v5
	v_bfe_u32 v138, v129, 5, 1
	ds_read_b128 v[64:67], v173 offset:32768
	ds_read_b128 v[68:71], v173 offset:40960
	ds_read_b128 v[72:75], v173 offset:49152
	ds_read_b128 v[76:79], v173 offset:57344
	ds_read_b128 v[96:99], v173
	ds_read_b128 v[100:103], v173 offset:8192
	ds_read_b128 v[104:107], v173 offset:16384
	ds_read_b128 v[108:111], v173 offset:24576
	s_waitcnt lgkmcnt(4)
	ds_write_b128 v142, v[64:67] offset:16384
	ds_write_b128 v142, v[68:71] offset:24576
	ds_write_b128 v142, v[72:75]
	ds_write_b128 v142, v[76:79] offset:8192
	v_addc_co_u32_e32 v3, vcc, 0, v133, vcc
	global_load_dwordx4 v[112:115], v[2:3], off offset:2048
	global_load_dwordx4 v[116:119], v[0:1], off offset:128
	v_bitop3_b32 v0, v40, v138, 7 bitop3:0x6c
	v_lshlrev_b32_e32 v143, 7, v5
	v_lshlrev_b32_e32 v145, 4, v0
	s_waitcnt lgkmcnt(0)
	s_barrier
	v_or_b32_e32 v41, v143, v145
	v_or_b32_e32 v32, 2, v138
	v_bitop3_b32 v32, v40, v32, 7 bitop3:0x6c
	v_lshlrev_b32_e32 v146, 4, v32
	v_or_b32_e32 v42, v143, v146
	v_or_b32_e32 v32, 4, v138
	v_bitop3_b32 v32, v40, v32, 7 bitop3:0x6c
	v_lshlrev_b32_e32 v147, 4, v32
	v_or_b32_e32 v43, v143, v147
	v_or_b32_e32 v32, 6, v138
	v_bitop3_b32 v32, v40, v32, 7 bitop3:0x6c
	v_lshlrev_b32_e32 v149, 4, v32
	v_or_b32_e32 v72, v143, v149
	ds_read_b128 v[178:181], v41 offset:16384
	ds_read_b128 v[182:185], v41 offset:20480
	ds_read_b128 v[186:189], v42 offset:16384
	ds_read_b128 v[190:193], v42 offset:20480
	ds_read_b128 v[194:197], v43 offset:16384
	ds_read_b128 v[198:201], v43 offset:20480
	ds_read_b128 v[202:205], v72 offset:16384
	ds_read_b128 v[206:209], v72 offset:20480
	v_lshrrev_b32_e32 v73, 5, v129
	v_bfe_u32 v74, v129, 1, 3
	s_lshr_b32 s2, s21, 6
	v_mad_i64_i32 v[134:135], s[18:19], v128, s33, 0
	s_add_i32 s2, s2, -1
	v_and_b32_e32 v148, 31, v129
	v_lshlrev_b32_e32 v75, 7, v148
	s_mov_b32 s3, 5
	s_waitcnt lgkmcnt(7)
	v_mfma_f32_32x32x16_bf16 v[16:31], v[178:181], v[96:99], 0
	s_waitcnt lgkmcnt(6)
	v_mfma_f32_32x32x16_bf16 v[0:15], v[182:185], v[96:99], 0
	s_waitcnt lgkmcnt(5)
	v_mfma_f32_32x32x16_bf16 v[16:31], v[186:189], v[100:103], v[16:31]
	s_waitcnt lgkmcnt(4)
	v_mfma_f32_32x32x16_bf16 v[0:15], v[190:193], v[100:103], v[0:15]
	s_waitcnt lgkmcnt(3)
	v_mfma_f32_32x32x16_bf16 v[16:31], v[194:197], v[104:107], v[16:31]
	s_waitcnt lgkmcnt(2)
	v_mfma_f32_32x32x16_bf16 v[0:15], v[198:201], v[104:107], v[0:15]
	s_waitcnt lgkmcnt(1)
	v_mfma_f32_32x32x16_bf16 v[16:31], v[202:205], v[108:111], v[16:31]
	s_waitcnt lgkmcnt(0)
	v_mfma_f32_32x32x16_bf16 v[0:15], v[206:209], v[108:111], v[0:15]
	s_nop 9
	v_exp_f32_e32 v32, v16
	v_exp_f32_e32 v33, v17
	v_exp_f32_e32 v34, v18
	v_exp_f32_e32 v35, v19
	v_exp_f32_e32 v37, v20
	v_exp_f32_e32 v38, v21
	v_add_f32_e32 v16, 0, v32
	v_add_f32_e32 v17, 0, v33
	v_add_f32_e32 v36, 0, v34
	v_add_f32_e32 v39, 0, v35
	v_add_f32_e32 v40, v37, v16
	v_add_f32_e32 v44, v38, v17
	v_exp_f32_e32 v45, v22
	v_exp_f32_e32 v46, v23
	ds_read_b128 v[16:19], v41 offset:24576
	ds_read_b128 v[20:23], v41 offset:28672
	s_waitcnt lgkmcnt(1)
	v_mfma_f32_32x32x16_bf16 v[48:63], v[16:19], v[96:99], 0
	v_exp_f32_e32 v41, v24
	v_add_f32_e32 v36, v45, v36
	v_add_f32_e32 v39, v46, v39
	ds_read_b128 v[64:67], v42 offset:24576
	ds_read_b128 v[68:71], v42 offset:28672
	v_exp_f32_e32 v42, v25
	v_add_f32_e32 v24, v41, v40
	v_exp_f32_e32 v40, v26
	v_exp_f32_e32 v47, v27
	v_exp_f32_e32 v28, v28
	v_exp_f32_e32 v29, v29
	v_exp_f32_e32 v30, v30
	v_exp_f32_e32 v31, v31
	v_exp_f32_e32 v77, v0
	v_exp_f32_e32 v78, v1
	v_add_f32_e32 v25, v42, v44
	s_waitcnt lgkmcnt(1)
	v_mfma_f32_32x32x16_bf16 v[48:63], v[64:67], v[100:103], v[48:63]
	v_add_f32_e32 v26, v40, v36
	v_add_f32_e32 v27, v47, v39
	v_cvt_pk_bf16_f32 v80, v32, v33
	v_cvt_pk_bf16_f32 v81, v34, v35
	v_cvt_pk_bf16_f32 v82, v37, v38
	v_cvt_pk_bf16_f32 v83, v45, v46
	v_add_f32_e32 v24, v28, v24
	v_add_f32_e32 v25, v29, v25
	v_exp_f32_e32 v4, v4
	v_add_f32_e32 v76, v30, v26
	v_add_f32_e32 v0, v31, v27
	v_add_f32_e32 v79, v77, v24
	v_add_f32_e32 v88, v78, v25
	ds_read_b128 v[16:19], v43 offset:24576
	ds_read_b128 v[24:27], v43 offset:28672
	v_cvt_pk_bf16_f32 v86, v28, v29
	v_exp_f32_e32 v28, v2
	v_exp_f32_e32 v29, v3
	v_exp_f32_e32 v5, v5
	s_waitcnt lgkmcnt(1)
	v_mfma_f32_32x32x16_bf16 v[48:63], v[16:19], v[104:107], v[48:63]
	v_cvt_pk_bf16_f32 v84, v41, v42
	v_cvt_pk_bf16_f32 v85, v40, v47
	v_exp_f32_e32 v6, v6
	v_exp_f32_e32 v7, v7
	v_cvt_pk_bf16_f32 v87, v30, v31
	v_add_f32_e32 v30, v28, v76
	v_add_f32_e32 v31, v29, v0
	v_mfma_f32_32x32x16_bf16 v[32:47], v[20:23], v[96:99], 0
	ds_read_b128 v[0:3], v72 offset:24576
	ds_read_b128 v[20:23], v72 offset:28672
	v_add_f32_e32 v64, v4, v79
	v_add_f32_e32 v65, v5, v88
	v_add_f32_e32 v30, v6, v30
	v_exp_f32_e32 v8, v8
	v_exp_f32_e32 v9, v9
	v_add_f32_e32 v31, v7, v31
	v_cvt_pk_bf16_f32 v90, v4, v5
	v_exp_f32_e32 v4, v10
	v_exp_f32_e32 v5, v11
	v_exp_f32_e32 v11, v13
	v_cvt_pk_bf16_f32 v91, v6, v7
	v_exp_f32_e32 v7, v12
	s_waitcnt lgkmcnt(1)
	v_mfma_f32_32x32x16_bf16 v[48:63], v[0:3], v[108:111], v[48:63]
	v_exp_f32_e32 v0, v14
	v_exp_f32_e32 v1, v15
	v_add_f32_e32 v64, v8, v64
	v_add_f32_e32 v65, v9, v65
	v_cvt_pk_bf16_f32 v88, v77, v78
	v_cvt_pk_bf16_f32 v89, v28, v29
	v_add_f32_e32 v6, v4, v30
	v_mfma_f32_32x32x16_bf16 v[32:47], v[68:71], v[100:103], v[32:47]
	v_add_f32_e32 v10, v5, v31
	v_mov_b32_e32 v16, 0
	v_add_f32_e32 v12, v7, v64
	v_add_f32_e32 v2, v11, v65
	v_add_f32_e32 v3, v0, v6
	v_add_f32_e32 v6, v1, v10
	v_mfma_f32_32x32x16_bf16 v[32:47], v[24:27], v[104:107], v[32:47]
	v_cvt_pk_bf16_f32 v95, v0, v1
	v_add_f32_e32 v0, v12, v2
	v_add_f32_e32 v1, v3, v6
	v_add_f32_e32 v0, v0, v1
	v_add_f32_e32 v150, 0, v0
	v_bitop3_b32 v0, v73, v74, 1 bitop3:0x6c
	v_lshlrev_b32_e32 v2, 4, v0
	v_bitop3_b32 v0, v138, v74, 2 bitop3:0x36
	v_lshlrev_b32_e32 v3, 4, v0
	v_bitop3_b32 v0, v138, v74, 4 bitop3:0x36
	v_cvt_pk_bf16_f32 v93, v4, v5
	v_lshlrev_b32_e32 v4, 4, v0
	v_bitop3_b32 v0, v138, v74, 6 bitop3:0x36
	v_lshlrev_b32_e32 v5, 4, v0
	v_and_b32_e32 v0, 7, v129
	v_cvt_pk_bf16_f32 v92, v8, v9
	v_cvt_pk_bf16_f32 v94, v7, v11
	v_lshlrev_b32_e32 v176, 4, v0
	v_lshlrev_b32_e32 v0, 1, v128
	s_waitcnt lgkmcnt(0)
	s_barrier
	v_mad_i64_i32 v[0:1], s[18:19], v0, s21, v[176:177]
	s_add_u32 s18, s9, s38
	v_readlane_b32 s9, v254, 53
	s_addc_u32 s19, s9, s39
	s_waitcnt lgkmcnt(0)
	v_mfma_f32_32x32x16_bf16 v[32:47], v[20:23], v[108:111], v[32:47]
	v_lshl_add_u64 v[136:137], s[18:19], 0, v[0:1]
	v_add_u32_e32 v144, v75, v2
	v_add_u32_e32 v141, v75, v3
	v_add_u32_e32 v140, v75, v4
	v_add_u32_e32 v139, v75, v5
	v_mov_b32_e32 v17, v16
	v_mov_b32_e32 v18, v16
	v_mov_b32_e32 v19, v16
	v_mov_b32_e32 v20, v16
	v_mov_b32_e32 v21, v16
	v_mov_b32_e32 v22, v16
	v_mov_b32_e32 v23, v16
	v_mov_b32_e32 v24, v16
	v_mov_b32_e32 v25, v16
	v_mov_b32_e32 v26, v16
	v_mov_b32_e32 v27, v16
	v_mov_b32_e32 v28, v16
	v_mov_b32_e32 v29, v16
	v_mov_b32_e32 v30, v16
	v_mov_b32_e32 v31, v16
	v_mov_b32_e32 v0, v16
	v_mov_b32_e32 v1, v16
	v_mov_b32_e32 v2, v16
	v_mov_b32_e32 v3, v16
	v_mov_b32_e32 v4, v16
	v_mov_b32_e32 v5, v16
	v_mov_b32_e32 v6, v16
	v_mov_b32_e32 v7, v16
	v_mov_b32_e32 v8, v16
	v_mov_b32_e32 v9, v16
	v_mov_b32_e32 v10, v16
	v_mov_b32_e32 v11, v16
	v_mov_b32_e32 v12, v16
	v_mov_b32_e32 v13, v16
	v_mov_b32_e32 v14, v16
	v_mov_b32_e32 v15, v16
	v_add_u32_e32 v164, v143, v145
	v_add_u32_e32 v165, v143, v146
	v_add_u32_e32 v166, v143, v147
	v_add_u32_e32 v167, v143, v149
